# attention: skewed waves 4-7 run at static s_setprio 2 through the tile loop (they were the arbitration losers / critical path)
# baseline (speedup 1.0000x reference)
; __device__ __forceinline__ void attn_phase(LAS unsigned char* lds, const bf16_t* QKV, const float* kmean, const float* biasT, bf16_t* O, int G, int wg) {
;     ...
;     for (int u = wg; u < 1024; u += G) {
;         const int k4 = u >> 8, w8 = u & 255, half = w8 >> 7, bh = w8 & 127, b = bh >> 3, h = bh & 7;
;         const int ob = half ? ((k4 == 0) ? 6 : (k4 == 1) ? 1 : (k4 == 2) ? 4 : 3) : ((k4 == 0) ? 7 : (k4 == 1) ? 0 : (k4 == 2) ? 5 : 2);
.LBB0_1309:
	s_setprio 0
	s_ashr_i32 s16, s53, 8
	s_and_b32 s46, s53, 0x80
	s_cmpk_lt_u32 s53, 0x100
	s_cselect_b64 s[0:1], -1, 0
	s_cmp_eq_u32 s16, 1
	s_cselect_b64 s[38:39], -1, 0
	s_cmp_eq_u32 s16, 2
	s_cselect_b64 s[44:45], -1, 0
	s_cmp_eq_u32 s46, 0
	s_mov_b64 s[46:47], -1
	s_cbranch_scc1 .LBB0_1311
	s_and_b64 s[46:47], s[44:45], exec
	s_cselect_b32 s16, 4, 3
	s_and_b64 s[46:47], s[38:39], exec
	s_cselect_b32 s16, 1, s16
	s_and_b64 s[46:47], s[0:1], exec
	s_cselect_b32 s54, 6, s16
	s_mov_b64 s[46:47], 0

; #define LAS __attribute__((address_space(3)))
; #define LDS_BARRIER() asm volatile("s_waitcnt lgkmcnt(0)\n\ts_barrier" ::: "memory")
; __device__ __forceinline__ void attn_phase(LAS unsigned char* lds, const bf16_t* QKV, const float* kmean, const float* biasT, bf16_t* O, int G, int wg) {
;     ...
;         for (int ti = 0; ti < nTiles; ++ti) {
;             const bool own = ti < 4; const int r_ = ti - 4; const int blk = own ? ob : (r_ >> 2), kt = own ? ti : (r_ & 3);
;             const int key0 = blk * 256 + kt * 64;
;             LDS_BARRIER();
;             const int nxt = (cur == 2) ? 0 : cur + 1;
;             if (ti + 1 < nTiles) { ATT_STAGE(nxt); if (ti + 2 < nTiles) ATT_LOAD(ti + 2); }
;             const LAS unsigned char* sb = lds + cur * STAGE;
;             if (pend) { ATT_PV(lds + pend_buf * STAGE); pend = false; }
;             const int cur_ = cur; cur = nxt;
;             if (own && kt * 64 > wid * 32 + 31) continue;
;             f32x4 sc[2][4];
;             __builtin_amdgcn_s_setprio(1);
.LBB0_1354:
	s_and_saveexec_b64 s[44:45], s[38:39]
	s_cbranch_execz .LBB0_1356
	s_setprio 2
	v_mad_u64_u32 v[132:133], s[48:49], v232, s93, v[168:169]
	v_add_u32_e32 v133, 0x4000, v132
	ds_read2_b64 v[128:131], v133 offset1:4
	s_waitcnt lgkmcnt(0)
	v_mfma_f32_16x16x32_bf16 v[92:95], v[128:131], v[112:115], v[92:95]
	v_mfma_f32_16x16x32_bf16 v[60:63], v[128:131], v[120:123], v[60:63]
	ds_read2_b64 v[128:131], v133 offset0:8 offset1:12
	v_add_u32_e32 v133, 0x4800, v132
	s_waitcnt lgkmcnt(0)
	v_mfma_f32_16x16x32_bf16 v[92:95], v[128:131], v[116:119], v[92:95]
	v_mfma_f32_16x16x32_bf16 v[60:63], v[128:131], v[124:127], v[60:63]
	ds_read2_b64 v[128:131], v133 offset0:16 offset1:20
	s_waitcnt lgkmcnt(0)
	v_mfma_f32_16x16x32_bf16 v[88:91], v[128:131], v[112:115], v[88:91]
	v_mfma_f32_16x16x32_bf16 v[56:59], v[128:131], v[120:123], v[56:59]
	ds_read2_b64 v[128:131], v133 offset0:24 offset1:28
	s_waitcnt lgkmcnt(0)
	v_mfma_f32_16x16x32_bf16 v[88:91], v[128:131], v[116:119], v[88:91]
	v_mfma_f32_16x16x32_bf16 v[56:59], v[128:131], v[124:127], v[56:59]
	v_add_u32_e32 v133, 0x5000, v132
	ds_read2_b64 v[128:131], v133 offset0:32 offset1:36
	s_waitcnt lgkmcnt(0)
	v_mfma_f32_16x16x32_bf16 v[84:87], v[128:131], v[112:115], v[84:87]
	v_mfma_f32_16x16x32_bf16 v[52:55], v[128:131], v[120:123], v[52:55]
	ds_read2_b64 v[128:131], v133 offset0:40 offset1:44
	v_add_u32_e32 v133, 0x5800, v132
	s_waitcnt lgkmcnt(0)
	v_mfma_f32_16x16x32_bf16 v[84:87], v[128:131], v[116:119], v[84:87]
	v_mfma_f32_16x16x32_bf16 v[52:55], v[128:131], v[124:127], v[52:55]
	ds_read2_b64 v[128:131], v133 offset0:48 offset1:52
	s_waitcnt lgkmcnt(0)
	v_mfma_f32_16x16x32_bf16 v[80:83], v[128:131], v[112:115], v[80:83]
	v_mfma_f32_16x16x32_bf16 v[48:51], v[128:131], v[120:123], v[48:51]
	ds_read2_b64 v[128:131], v133 offset0:56 offset1:60
	s_waitcnt lgkmcnt(0)
	v_mfma_f32_16x16x32_bf16 v[80:83], v[128:131], v[116:119], v[80:83]
	v_mfma_f32_16x16x32_bf16 v[48:51], v[128:131], v[124:127], v[48:51]
	v_add_u32_e32 v133, 0x6000, v132
	ds_read2_b64 v[128:131], v133 offset0:64 offset1:68
	s_waitcnt lgkmcnt(0)
	v_mfma_f32_16x16x32_bf16 v[76:79], v[128:131], v[112:115], v[76:79]
	v_mfma_f32_16x16x32_bf16 v[44:47], v[128:131], v[120:123], v[44:47]
	ds_read2_b64 v[128:131], v133 offset0:72 offset1:76
	v_add_u32_e32 v133, 0x6800, v132
	s_waitcnt lgkmcnt(0)
	v_mfma_f32_16x16x32_bf16 v[76:79], v[128:131], v[116:119], v[76:79]
	v_mfma_f32_16x16x32_bf16 v[44:47], v[128:131], v[124:127], v[44:47]
	ds_read2_b64 v[128:131], v133 offset0:80 offset1:84
	s_waitcnt lgkmcnt(0)
	v_mfma_f32_16x16x32_bf16 v[72:75], v[128:131], v[112:115], v[72:75]
	v_mfma_f32_16x16x32_bf16 v[40:43], v[128:131], v[120:123], v[40:43]
	ds_read2_b64 v[128:131], v133 offset0:88 offset1:92
	s_waitcnt lgkmcnt(0)
	v_mfma_f32_16x16x32_bf16 v[72:75], v[128:131], v[116:119], v[72:75]
	v_mfma_f32_16x16x32_bf16 v[40:43], v[128:131], v[124:127], v[40:43]
	v_add_u32_e32 v133, 0x7000, v132
	ds_read2_b64 v[128:131], v133 offset0:96 offset1:100
	v_add_u32_e32 v132, 0x7800, v132
	s_waitcnt lgkmcnt(0)
	v_mfma_f32_16x16x32_bf16 v[68:71], v[128:131], v[112:115], v[68:71]
	v_mfma_f32_16x16x32_bf16 v[36:39], v[128:131], v[120:123], v[36:39]
	ds_read2_b64 v[128:131], v133 offset0:104 offset1:108
	s_waitcnt lgkmcnt(0)
	v_mfma_f32_16x16x32_bf16 v[68:71], v[128:131], v[116:119], v[68:71]
	v_mfma_f32_16x16x32_bf16 v[36:39], v[128:131], v[124:127], v[36:39]
	ds_read2_b64 v[128:131], v132 offset0:112 offset1:116
	s_waitcnt lgkmcnt(0)
	v_mfma_f32_16x16x32_bf16 v[64:67], v[128:131], v[112:115], v[64:67]
	v_mfma_f32_16x16x32_bf16 v[32:35], v[128:131], v[120:123], v[32:35]
	ds_read2_b64 v[128:131], v132 offset0:120 offset1:124
	s_waitcnt lgkmcnt(0)
	v_mfma_f32_16x16x32_bf16 v[64:67], v[128:131], v[116:119], v[64:67]
	v_mfma_f32_16x16x32_bf16 v[32:35], v[128:131], v[124:127], v[32:35]
.LBB0_1356:
	s_or_b64 exec, exec, s[44:45]
	s_and_b32 s44, s56, 0xc0
	s_xor_b64 s[50:51], s[0:1], -1
	v_cmp_le_i32_e32 vcc, s44, v221
	s_or_b64 s[60:61], s[50:51], vcc
	s_andn2_b64 s[38:39], s[38:39], exec
	s_and_saveexec_b64 s[48:49], s[60:61]
	s_cbranch_execz .LBB0_1372
	s_mul_i32 s45, s59, 0x8800
	s_add_i32 s60, s45, 0
	s_ashr_i32 s45, s57, 2
	s_and_b64 s[0:1], s[0:1], exec
	s_cselect_b32 s0, s54, s45
	s_lshl_b32 s1, s0, 8
	v_mov_b32_e32 v209, v210
	s_or_b32 s62, s1, s44
	s_cmp_eq_u64 s[40:41], 0
	s_cbranch_scc1 .Lprio_qk_skew
	s_setprio 1
	s_branch .Lprio_qk_go
.Lprio_qk_skew:
	s_setprio 2
; #define LAS __attribute__((address_space(3)))
; #define MFMA16(a, b, c) __builtin_amdgcn_mfma_f32_16x16x32_bf16((a), (b), (c), 0, 0, 0)
; __device__ __forceinline__ void attn_phase(LAS unsigned char* lds, const bf16_t* QKV, const float* kmean, const float* biasT, bf16_t* O, int G, int wg) {
;     ...
;             __builtin_amdgcn_s_setprio(1);
; #pragma unroll
;             for (int st = 0; st < 4; ++st) { sc[0][st] = (f32x4){0.f, 0.f, 0.f, 0.f}; sc[1][st] = (f32x4){0.f, 0.f, 0.f, 0.f};
; #pragma unroll
;                 for (int ks = 0; ks < 4; ++ks) { const bf16x8 af = *(const LAS bf16x8*)(sb + KS_OFF + st * 4096 + (LK0 ^ (ks << 6)));
;                     sc[0][st] = MFMA16(af, qf[0][ks], sc[0][st]); sc[1][st] = MFMA16(af, qf[1][ks], sc[1][st]); }
;                 __builtin_amdgcn_sched_barrier(0); }
;             __builtin_amdgcn_s_setprio(0);
; #pragma unroll
;             for (int z = 0; z < 2; ++z) {
;                 const int tq = tq0 + 16 * z;
;                 const bool selok = (selmask[z] >> blk) & 1u;
;                 float mx = -1e30f;
;                 if (own) {
; #pragma unroll
;                     for (int st = 0; st < 4; ++st)
; #pragma unroll
;                         for (int j = 0; j < 4; ++j) { const int dist = tq - (key0 + st * 16 + fq * 4 + j);
;                             float s = sc[z][st][j] + BT[dist < 0 ? 0 : dist]; s = (dist >= 0) ? s : -1e30f; sc[z][st][j] = s; mx = fmaxf(mx, s); }
;                 } else {
;                     const LAS float* bp = BT + (tq0 - key0 - fq * 4 - 63);
; #pragma unroll
;                     for (int st = 0; st < 4; ++st)
; #pragma unroll
;                         for (int j = 0; j < 4; ++j) { const float s = sc[z][st][j] + bp[63 - st * 16 - j + 16 * z]; sc[z][st][j] = s; mx = fmaxf(mx, s); }
;                     mx = selok ? mx : -1e30f;
.Lprio_qk_go:
	v_add_u32_e32 v172, s60, v183
	ds_read_b128 v[112:115], v172
	v_add_u32_e32 v173, s60, v224
	ds_read_b128 v[120:123], v173
	v_add_u32_e32 v186, s60, v225
	v_add_u32_e32 v187, s60, v226
	s_waitcnt vmcnt(11) lgkmcnt(1)
	v_mfma_f32_16x16x32_bf16 v[116:119], v[112:115], v[0:3], 0
	s_waitcnt vmcnt(5)
	v_mfma_f32_16x16x32_bf16 v[112:115], v[112:115], v[24:27], 0
	s_waitcnt lgkmcnt(0)
	v_mfma_f32_16x16x32_bf16 v[116:119], v[120:123], v[4:7], v[116:119]
	v_mfma_f32_16x16x32_bf16 v[112:115], v[120:123], v[16:19], v[112:115]
	ds_read_b128 v[120:123], v186
	s_waitcnt lgkmcnt(0)
	v_mfma_f32_16x16x32_bf16 v[116:119], v[120:123], v[8:11], v[116:119]
	v_mfma_f32_16x16x32_bf16 v[112:115], v[120:123], v[20:23], v[112:115]
	ds_read_b128 v[120:123], v187
	s_waitcnt lgkmcnt(0)
	v_mfma_f32_16x16x32_bf16 v[140:143], v[120:123], v[12:15], v[116:119]
	s_waitcnt vmcnt(4)
	v_mfma_f32_16x16x32_bf16 v[124:127], v[120:123], v[28:31], v[112:115]
	s_nop 2
	ds_read_b128 v[112:115], v172 offset:4096
	ds_read_b128 v[120:123], v173 offset:4096
	s_waitcnt lgkmcnt(1)
	v_mfma_f32_16x16x32_bf16 v[116:119], v[112:115], v[0:3], 0
	v_mfma_f32_16x16x32_bf16 v[112:115], v[112:115], v[24:27], 0
	s_waitcnt lgkmcnt(0)
	v_mfma_f32_16x16x32_bf16 v[116:119], v[120:123], v[4:7], v[116:119]
	v_mfma_f32_16x16x32_bf16 v[112:115], v[120:123], v[16:19], v[112:115]
	ds_read_b128 v[120:123], v186 offset:4096
	s_waitcnt lgkmcnt(0)
	v_mfma_f32_16x16x32_bf16 v[116:119], v[120:123], v[8:11], v[116:119]
	v_mfma_f32_16x16x32_bf16 v[112:115], v[120:123], v[20:23], v[112:115]
	ds_read_b128 v[120:123], v187 offset:4096
	s_waitcnt lgkmcnt(0)
	v_mfma_f32_16x16x32_bf16 v[136:139], v[120:123], v[12:15], v[116:119]
	v_mfma_f32_16x16x32_bf16 v[120:123], v[120:123], v[28:31], v[112:115]
	s_nop 3
	ds_read_b128 v[112:115], v172 offset:8192
	ds_read_b128 v[128:131], v173 offset:8192
	s_waitcnt lgkmcnt(1)
	v_mfma_f32_16x16x32_bf16 v[116:119], v[112:115], v[0:3], 0
	v_mfma_f32_16x16x32_bf16 v[112:115], v[112:115], v[24:27], 0
	s_waitcnt lgkmcnt(0)
	v_mfma_f32_16x16x32_bf16 v[116:119], v[128:131], v[4:7], v[116:119]
	v_mfma_f32_16x16x32_bf16 v[112:115], v[128:131], v[16:19], v[112:115]
	ds_read_b128 v[128:131], v186 offset:8192
	s_waitcnt lgkmcnt(0)
	v_mfma_f32_16x16x32_bf16 v[116:119], v[128:131], v[8:11], v[116:119]
	v_mfma_f32_16x16x32_bf16 v[112:115], v[128:131], v[20:23], v[112:115]
	ds_read_b128 v[128:131], v187 offset:8192
	s_waitcnt lgkmcnt(0)
	v_mfma_f32_16x16x32_bf16 v[132:135], v[128:131], v[12:15], v[116:119]
	v_mfma_f32_16x16x32_bf16 v[116:119], v[128:131], v[28:31], v[112:115]
	s_nop 3
	ds_read_b128 v[112:115], v172 offset:12288
	ds_read_b128 v[176:179], v173 offset:12288
	s_waitcnt lgkmcnt(1)
	v_mfma_f32_16x16x32_bf16 v[128:131], v[112:115], v[0:3], 0
	v_mfma_f32_16x16x32_bf16 v[112:115], v[112:115], v[24:27], 0
	s_waitcnt lgkmcnt(0)
	v_mfma_f32_16x16x32_bf16 v[128:131], v[176:179], v[4:7], v[128:131]
	v_mfma_f32_16x16x32_bf16 v[112:115], v[176:179], v[16:19], v[112:115]
	ds_read_b128 v[176:179], v186 offset:12288
	s_waitcnt lgkmcnt(0)
	v_mfma_f32_16x16x32_bf16 v[128:131], v[176:179], v[8:11], v[128:131]
	v_mfma_f32_16x16x32_bf16 v[112:115], v[176:179], v[20:23], v[112:115]
	ds_read_b128 v[176:179], v187 offset:12288
	s_waitcnt lgkmcnt(0)
	v_mfma_f32_16x16x32_bf16 v[128:131], v[176:179], v[12:15], v[128:131]
	v_mfma_f32_16x16x32_bf16 v[112:115], v[176:179], v[28:31], v[112:115]
	s_cmp_eq_u64 s[40:41], 0
	s_cbranch_scc1 .Lprio_qk_end
	s_setprio 0
.Lprio_qk_end:
	v_or_b32_e32 v236, s62, v222
	v_sub_u32_e32 v203, v180, v236
	v_lshl_add_u32 v250, v203, 2, s88
	s_lshl_b32 s61, 1, s0
	s_mov_b64 s[44:45], -1
	s_and_b64 vcc, exec, s[50:51]
	v_add_u32_e32 v249, -4, v250
	v_add_u32_e32 v246, -12, v250
	v_add_u32_e32 v245, 0xffffffbc, v250
	v_add_u32_e32 v244, 0xffffffb4, v250
	v_add_u32_e32 v243, 0xffffff7c, v250
	v_add_u32_e32 v204, 0xffffff74, v250
	s_cbranch_vccz .LBB0_1359
	v_and_b32_e32 v172, s61, v230
	v_cmp_ne_u32_e64 s[0:1], 0, v172
	ds_read2_b32 v[172:173], v249 offset1:1
	s_mov_b64 s[44:45], 0
	s_waitcnt lgkmcnt(0)
	v_pk_add_f32 v[186:187], v[140:141], v[172:173] op_sel:[0,1] op_sel_hi:[1,0]
	ds_read2_b32 v[172:173], v246 offset1:1
	v_max3_f32 v176, v186, s90, v187
	s_waitcnt lgkmcnt(0)
	v_pk_add_f32 v[188:189], v[142:143], v[172:173] op_sel:[0,1] op_sel_hi:[1,0]
	ds_read2_b32 v[172:173], v245 offset1:1
	v_max3_f32 v176, v176, v188, v189
	s_waitcnt lgkmcnt(0)
	v_pk_add_f32 v[190:191], v[136:137], v[172:173] op_sel:[0,1] op_sel_hi:[1,0]
	ds_read2_b32 v[172:173], v244 offset1:1
	v_max3_f32 v176, v176, v190, v191
	s_waitcnt lgkmcnt(0)
	v_pk_add_f32 v[192:193], v[138:139], v[172:173] op_sel:[0,1] op_sel_hi:[1,0]
	ds_read2_b32 v[172:173], v243 offset1:1
	v_max3_f32 v176, v176, v192, v193
	s_waitcnt lgkmcnt(0)
	v_pk_add_f32 v[194:195], v[132:133], v[172:173] op_sel:[0,1] op_sel_hi:[1,0]
	ds_read2_b32 v[172:173], v204 offset1:1
	v_max3_f32 v176, v176, v194, v195
	s_waitcnt lgkmcnt(0)
	v_pk_add_f32 v[196:197], v[134:135], v[172:173] op_sel:[0,1] op_sel_hi:[1,0]
	v_add_u32_e32 v172, 0xffffff3c, v250
	ds_read2_b32 v[172:173], v172 offset1:1
	v_max3_f32 v176, v176, v196, v197
	s_waitcnt lgkmcnt(0)
	v_pk_add_f32 v[198:199], v[128:129], v[172:173] op_sel:[0,1] op_sel_hi:[1,0]
	v_add_u32_e32 v172, 0xffffff34, v250
	ds_read2_b32 v[172:173], v172 offset1:1
	v_max3_f32 v176, v176, v198, v199
	s_waitcnt lgkmcnt(0)
	v_pk_add_f32 v[200:201], v[130:131], v[172:173] op_sel:[0,1] op_sel_hi:[1,0]
	s_nop 0
	v_max3_f32 v172, v176, v200, v201
	v_cndmask_b32_e64 v205, v215, v172, s[0:1]
